# decode per-head path: permlane32_swap for the cross-half ssq sum + partner-score reads issued together (without the exp interleave)
# speedup vs baseline: 1.0021x; 1.0021x over previous
.LBB0_1552:
	s_or_b64 exec, exec, s[0:1]
	s_and_b32 s0, s12, 0x3c000
	s_lshl_b32 s0, s0, 1
	s_add_u32 s0, s64, s0
	s_addc_u32 s1, s65, 0
	v_lshl_add_u32 v6, v12, 4, s76
	v_lshl_add_u64 v[14:15], s[0:1], 0, v[6:7]
	v_add_co_u32_e32 v16, vcc, s87, v14
	global_load_dwordx4 v[138:141], v6, s[0:1]
	s_nop 0
	v_addc_co_u32_e32 v17, vcc, 0, v15, vcc
	global_load_dwordx4 v[142:145], v[16:17], off
	v_add_co_u32_e32 v16, vcc, s4, v14
	v_lshlrev_b32_e32 v13, 4, v244
	s_nop 0
	v_addc_co_u32_e32 v17, vcc, 0, v15, vcc
	v_add_co_u32_e32 v14, vcc, s5, v14
	global_load_dwordx4 v[146:149], v[16:17], off
	s_nop 0
	v_addc_co_u32_e32 v15, vcc, 0, v15, vcc
	global_load_dwordx4 v[150:153], v[14:15], off
	s_mul_i32 s0, s13, 0x8200
	s_add_i32 s0, s0, 0
	s_add_i32 s0, s0, s54
	v_mul_u32_u24_e32 v6, 0x410, v243
	s_add_i32 s0, s0, 0x10800
	v_add3_u32 v6, s0, v6, v13
	ds_read_b128 v[114:117], v6
	ds_read_b128 v[118:121], v6 offset:32
	ds_read_b128 v[122:125], v6 offset:64
	ds_read_b128 v[126:129], v6 offset:96
	ds_read_b128 v[14:17], v6 offset:128
	s_waitcnt lgkmcnt(4)
	v_mfma_f32_32x32x16_bf16 v[98:113], v[114:117], v[154:157], 0
	ds_read_b128 v[114:117], v6 offset:160
	s_waitcnt lgkmcnt(4)
	v_mfma_f32_32x32x16_bf16 v[98:113], v[118:121], v[158:161], v[98:113]
	ds_read_b128 v[118:121], v6 offset:192
	s_waitcnt lgkmcnt(4)
	v_mfma_f32_32x32x16_bf16 v[98:113], v[122:125], v[162:165], v[98:113]
	ds_read_b128 v[122:125], v6 offset:224
	s_waitcnt lgkmcnt(4)
	v_mfma_f32_32x32x16_bf16 v[98:113], v[126:129], v[166:169], v[98:113]
	ds_read_b128 v[126:129], v6 offset:256
	s_waitcnt lgkmcnt(4)
	v_mfma_f32_32x32x16_bf16 v[98:113], v[14:17], v[170:173], v[98:113]
	ds_read_b128 v[14:17], v6 offset:288
	s_waitcnt lgkmcnt(4)
	v_mfma_f32_32x32x16_bf16 v[98:113], v[114:117], v[174:177], v[98:113]
	ds_read_b128 v[114:117], v6 offset:320
	s_waitcnt lgkmcnt(4)
	v_mfma_f32_32x32x16_bf16 v[98:113], v[118:121], v[178:181], v[98:113]
	ds_read_b128 v[118:121], v6 offset:352
	s_waitcnt lgkmcnt(4)
	v_mfma_f32_32x32x16_bf16 v[98:113], v[122:125], v[182:185], v[98:113]
	ds_read_b128 v[122:125], v6 offset:384
	s_waitcnt lgkmcnt(4)
	v_mfma_f32_32x32x16_bf16 v[98:113], v[126:129], v[186:189], v[98:113]
	ds_read_b128 v[126:129], v6 offset:416
	s_waitcnt lgkmcnt(4)
	v_mfma_f32_32x32x16_bf16 v[98:113], v[14:17], v[190:193], v[98:113]
	ds_read_b128 v[14:17], v6 offset:448
	s_waitcnt lgkmcnt(4)
	v_mfma_f32_32x32x16_bf16 v[98:113], v[114:117], v[194:197], v[98:113]
	ds_read_b128 v[114:117], v6 offset:480
	s_waitcnt lgkmcnt(4)
	v_mfma_f32_32x32x16_bf16 v[98:113], v[118:121], v[198:201], v[98:113]
	s_waitcnt lgkmcnt(3)
	v_mfma_f32_32x32x16_bf16 v[98:113], v[122:125], v[202:205], v[98:113]
	s_waitcnt lgkmcnt(2)
	v_mfma_f32_32x32x16_bf16 v[98:113], v[126:129], v[206:209], v[98:113]
	s_waitcnt lgkmcnt(1)
	v_mfma_f32_32x32x16_bf16 v[98:113], v[14:17], v[210:213], v[98:113]
	s_waitcnt lgkmcnt(0)
	v_mfma_f32_32x32x16_bf16 v[98:113], v[114:117], v[214:217], v[98:113]
	s_nop 11
	v_mul_f32_e32 v6, v99, v99
	v_fmac_f32_e32 v6, v98, v98
	v_fmac_f32_e32 v6, v100, v100
	v_fmac_f32_e32 v6, v101, v101
	v_fmac_f32_e32 v6, v102, v102
	v_fmac_f32_e32 v6, v103, v103
	v_fmac_f32_e32 v6, v104, v104
	v_cvt_pk_bf16_f32 v14, v98, v99
	v_cvt_pk_bf16_f32 v15, v100, v101
	v_cvt_pk_bf16_f32 v16, v102, v103
	v_cvt_pk_bf16_f32 v17, v104, v105
	v_fmac_f32_e32 v6, v105, v105
	s_waitcnt vmcnt(5)
	v_mfma_f32_32x32x16_bf16 v[114:129], v[8:11], v[14:17], 0
	v_fmac_f32_e32 v6, v106, v106
	v_fmac_f32_e32 v6, v107, v107
	v_fmac_f32_e32 v6, v108, v108
	v_fmac_f32_e32 v6, v109, v109
	v_fmac_f32_e32 v6, v110, v110
	v_fmac_f32_e32 v6, v111, v111
	v_fmac_f32_e32 v6, v112, v112
	v_cvt_pk_bf16_f32 v8, v106, v107
	v_cvt_pk_bf16_f32 v9, v108, v109
	v_cvt_pk_bf16_f32 v10, v110, v111
	v_cvt_pk_bf16_f32 v11, v112, v113
	v_fmac_f32_e32 v6, v113, v113
	s_waitcnt vmcnt(4)
	v_mfma_f32_32x32x16_bf16 v[114:129], v[2:5], v[8:11], v[114:129]
	v_mov_b32_e32 v245, v6
	s_mulk_i32 s13, 0x1400
	s_add_i32 s0, s77, s13
	v_cndmask_b32_e64 v3, 0, 1, s[28:29]
	v_cmp_ne_u32_e64 s[8:9], 1, v3
	v_permlane32_swap_b32_e32 v245, v6
	v_add_f32_e32 v2, v245, v6
	s_andn2_b64 vcc, exec, s[28:29]
	v_lshl_add_u32 v4, v12, 2, s0
	s_cbranch_vccnz .LBB0_1554
	s_nop 1
	ds_write2st64_b32 v4, v114, v115 offset1:1
	ds_write2st64_b32 v4, v116, v117 offset0:2 offset1:3
	ds_write_b32 v4, v2 offset:1024
.LBB0_1554:
	s_waitcnt lgkmcnt(0)
	s_barrier
	s_and_b64 vcc, exec, s[6:7]
	s_cbranch_vccnz .LBB0_1543
	ds_read_b32 v3, v4 offset:1024
	ds_read2st64_b32 v[246:247], v4 offset1:1
	ds_read2st64_b32 v[248:249], v4 offset0:2 offset1:3
	v_mov_b32_e32 v16, v7
	v_mov_b32_e32 v17, v7
	v_mov_b32_e32 v8, v7
	v_mov_b32_e32 v9, v7
	s_waitcnt lgkmcnt(2)
	v_add_f32_e32 v2, v2, v3
	v_fmamk_f32 v2, v2, 0x3c800000, v232
	v_rsq_f32_e32 v6, v2
	v_mov_b32_e32 v10, v7
	v_mov_b32_e32 v11, v7
	v_mov_b32_e32 v12, v7
	s_waitcnt lgkmcnt(1)
	v_pk_add_f32 v[2:3], v[114:115], v[246:247]
	s_waitcnt lgkmcnt(0)
	v_pk_add_f32 v[4:5], v[116:117], v[248:249]
	v_pk_mul_f32 v[2:3], v[2:3], v[6:7] op_sel_hi:[1,0]
	v_pk_mul_f32 v[4:5], v[6:7], v[4:5] op_sel_hi:[0,1]
	v_mov_b32_e32 v6, v7
	v_mov_b32_e32 v13, v7
	v_mov_b32_e32 v14, v7
	v_mov_b32_e32 v15, v7
	v_mov_b64_e32 v[112:113], v[16:17]
	v_mov_b64_e32 v[110:111], v[14:15]
	v_mov_b64_e32 v[108:109], v[12:13]
	v_mov_b64_e32 v[106:107], v[10:11]
	v_mov_b64_e32 v[104:105], v[8:9]
	v_mov_b64_e32 v[102:103], v[6:7]
	v_mov_b64_e32 v[100:101], v[4:5]
	v_mov_b64_e32 v[98:99], v[2:3]
	v_mul_lo_u32 v2, v244, s81
	v_lshl_or_b32 v2, v243, 1, v2
	v_mfma_f32_32x32x16_bf16 v[98:113], v[222:225], v[130:133], v[98:113]
	s_add_i32 s0, s11, s93
	v_add_u32_e32 v2, s0, v2
	v_add_u32_e32 v3, 0x25600, v2
	v_mfma_f32_32x32x16_bf16 v[98:113], v[218:221], v[134:137], v[98:113]
	s_nop 11
	v_sub_f32_e32 v4, v98, v230
	v_cmp_gt_f32_e32 vcc, s31, v4
	s_nop 1
	v_cndmask_b32_e32 v5, 0, v233, vcc
	v_add_f32_e32 v4, v4, v5
	v_exp_f32_e32 v4, v4
	v_cndmask_b32_e32 v5, 0, v241, vcc
	v_ldexp_f32 v4, v4, v5
	v_cvt_pk_bf16_f32 v4, v4, v7
	ds_write_b16 v3, v4
	v_sub_f32_e32 v3, v99, v230
	v_cmp_gt_f32_e32 vcc, s31, v3
	s_nop 1
	v_cndmask_b32_e32 v4, 0, v233, vcc
	v_add_f32_e32 v3, v3, v4
	v_exp_f32_e32 v3, v3
	v_cndmask_b32_e32 v4, 0, v241, vcc
	v_ldexp_f32 v3, v3, v4
	v_cvt_pk_bf16_f32 v3, v3, v7
	v_add_u32_e32 v4, 0x25710, v2
	ds_write_b16 v4, v3
	v_sub_f32_e32 v3, v100, v230
	v_cmp_gt_f32_e32 vcc, s31, v3
	s_nop 1
	v_cndmask_b32_e32 v4, 0, v233, vcc
	v_add_f32_e32 v3, v3, v4
	v_exp_f32_e32 v3, v3
	v_cndmask_b32_e32 v4, 0, v241, vcc
	v_ldexp_f32 v3, v3, v4
	v_cvt_pk_bf16_f32 v3, v3, v7
	v_add_u32_e32 v4, 0x25820, v2
	ds_write_b16 v4, v3
	v_sub_f32_e32 v3, v101, v230
	v_cmp_gt_f32_e32 vcc, s31, v3
	v_add_u32_e32 v2, 0x25930, v2
	s_nop 0
	v_cndmask_b32_e32 v4, 0, v233, vcc
	v_add_f32_e32 v3, v3, v4
	v_exp_f32_e32 v3, v3
	v_cndmask_b32_e32 v4, 0, v241, vcc
	v_ldexp_f32 v3, v3, v4
	v_cvt_pk_bf16_f32 v3, v3, v7
	ds_write_b16 v2, v3
	s_branch .LBB0_1543

.LBB0_1566:
	s_or_b64 exec, exec, s[0:1]
	s_and_b32 s0, s14, 0x3c000
	s_lshl_b32 s0, s0, 1
	s_add_u32 s0, s64, s0
	s_addc_u32 s1, s65, 0
	v_lshl_add_u32 v6, v12, 4, s76
	v_lshl_add_u64 v[14:15], s[0:1], 0, v[6:7]
	v_add_co_u32_e32 v16, vcc, s87, v14
	global_load_dwordx4 v[138:141], v6, s[0:1]
	s_nop 0
	v_addc_co_u32_e32 v17, vcc, 0, v15, vcc
	global_load_dwordx4 v[142:145], v[16:17], off
	v_add_co_u32_e32 v16, vcc, s4, v14
	v_lshlrev_b32_e32 v13, 4, v244
	s_nop 0
	v_addc_co_u32_e32 v17, vcc, 0, v15, vcc
	v_add_co_u32_e32 v14, vcc, s5, v14
	global_load_dwordx4 v[146:149], v[16:17], off
	s_nop 0
	v_addc_co_u32_e32 v15, vcc, 0, v15, vcc
	global_load_dwordx4 v[150:153], v[14:15], off
	s_mul_i32 s0, s15, 0x8200
	s_add_i32 s0, s0, 0
	s_add_i32 s0, s0, s54
	v_mul_u32_u24_e32 v6, 0x410, v243
	s_add_i32 s0, s0, 0x10800
	v_add3_u32 v6, s0, v6, v13
	ds_read_b128 v[114:117], v6
	ds_read_b128 v[118:121], v6 offset:32
	ds_read_b128 v[122:125], v6 offset:64
	ds_read_b128 v[126:129], v6 offset:96
	ds_read_b128 v[14:17], v6 offset:128
	s_waitcnt lgkmcnt(4)
	v_mfma_f32_32x32x16_bf16 v[98:113], v[114:117], v[154:157], 0
	ds_read_b128 v[114:117], v6 offset:160
	s_waitcnt lgkmcnt(4)
	v_mfma_f32_32x32x16_bf16 v[98:113], v[118:121], v[158:161], v[98:113]
	ds_read_b128 v[118:121], v6 offset:192
	s_waitcnt lgkmcnt(4)
	v_mfma_f32_32x32x16_bf16 v[98:113], v[122:125], v[162:165], v[98:113]
	ds_read_b128 v[122:125], v6 offset:224
	s_waitcnt lgkmcnt(4)
	v_mfma_f32_32x32x16_bf16 v[98:113], v[126:129], v[166:169], v[98:113]
	ds_read_b128 v[126:129], v6 offset:256
	s_waitcnt lgkmcnt(4)
	v_mfma_f32_32x32x16_bf16 v[98:113], v[14:17], v[170:173], v[98:113]
	ds_read_b128 v[14:17], v6 offset:288
	s_waitcnt lgkmcnt(4)
	v_mfma_f32_32x32x16_bf16 v[98:113], v[114:117], v[174:177], v[98:113]
	ds_read_b128 v[114:117], v6 offset:320
	s_waitcnt lgkmcnt(4)
	v_mfma_f32_32x32x16_bf16 v[98:113], v[118:121], v[178:181], v[98:113]
	ds_read_b128 v[118:121], v6 offset:352
	s_waitcnt lgkmcnt(4)
	v_mfma_f32_32x32x16_bf16 v[98:113], v[122:125], v[182:185], v[98:113]
	ds_read_b128 v[122:125], v6 offset:384
	s_waitcnt lgkmcnt(4)
	v_mfma_f32_32x32x16_bf16 v[98:113], v[126:129], v[186:189], v[98:113]
	ds_read_b128 v[126:129], v6 offset:416
	s_waitcnt lgkmcnt(4)
	v_mfma_f32_32x32x16_bf16 v[98:113], v[14:17], v[190:193], v[98:113]
	ds_read_b128 v[14:17], v6 offset:448
	s_waitcnt lgkmcnt(4)
	v_mfma_f32_32x32x16_bf16 v[98:113], v[114:117], v[194:197], v[98:113]
	ds_read_b128 v[114:117], v6 offset:480
	s_waitcnt lgkmcnt(4)
	v_mfma_f32_32x32x16_bf16 v[98:113], v[118:121], v[198:201], v[98:113]
	s_waitcnt lgkmcnt(3)
	v_mfma_f32_32x32x16_bf16 v[98:113], v[122:125], v[202:205], v[98:113]
	s_waitcnt lgkmcnt(2)
	v_mfma_f32_32x32x16_bf16 v[98:113], v[126:129], v[206:209], v[98:113]
	s_waitcnt lgkmcnt(1)
	v_mfma_f32_32x32x16_bf16 v[98:113], v[14:17], v[210:213], v[98:113]
	s_waitcnt lgkmcnt(0)
	v_mfma_f32_32x32x16_bf16 v[98:113], v[114:117], v[214:217], v[98:113]
	s_nop 11
	v_mul_f32_e32 v6, v99, v99
	v_fmac_f32_e32 v6, v98, v98
	v_fmac_f32_e32 v6, v100, v100
	v_fmac_f32_e32 v6, v101, v101
	v_fmac_f32_e32 v6, v102, v102
	v_fmac_f32_e32 v6, v103, v103
	v_fmac_f32_e32 v6, v104, v104
	v_cvt_pk_bf16_f32 v14, v98, v99
	v_cvt_pk_bf16_f32 v15, v100, v101
	v_cvt_pk_bf16_f32 v16, v102, v103
	v_cvt_pk_bf16_f32 v17, v104, v105
	v_fmac_f32_e32 v6, v105, v105
	s_waitcnt vmcnt(5)
	v_mfma_f32_32x32x16_bf16 v[114:129], v[8:11], v[14:17], 0
	v_fmac_f32_e32 v6, v106, v106
	v_fmac_f32_e32 v6, v107, v107
	v_fmac_f32_e32 v6, v108, v108
	v_fmac_f32_e32 v6, v109, v109
	v_fmac_f32_e32 v6, v110, v110
	v_fmac_f32_e32 v6, v111, v111
	v_fmac_f32_e32 v6, v112, v112
	v_cvt_pk_bf16_f32 v8, v106, v107
	v_cvt_pk_bf16_f32 v9, v108, v109
	v_cvt_pk_bf16_f32 v10, v110, v111
	v_cvt_pk_bf16_f32 v11, v112, v113
	v_fmac_f32_e32 v6, v113, v113
	s_waitcnt vmcnt(4)
	v_mfma_f32_32x32x16_bf16 v[114:129], v[2:5], v[8:11], v[114:129]
	v_mov_b32_e32 v245, v6
	s_mulk_i32 s15, 0x1400
	s_add_i32 s0, s77, s15
	s_and_b64 vcc, exec, s[8:9]
	v_lshl_add_u32 v4, v12, 2, s0
	v_permlane32_swap_b32_e32 v245, v6
	v_add_f32_e32 v2, v245, v6
	s_cbranch_vccnz .LBB0_1568
	s_nop 3
	ds_write2st64_b32 v4, v114, v115 offset1:1
	ds_write2st64_b32 v4, v116, v117 offset0:2 offset1:3
	ds_write_b32 v4, v2 offset:1024
.LBB0_1568:
	s_waitcnt lgkmcnt(0)
	s_barrier
	s_and_b64 vcc, exec, s[6:7]
	s_cbranch_vccnz .LBB0_1557
	ds_read_b32 v3, v4 offset:1024
	ds_read2st64_b32 v[246:247], v4 offset1:1
	ds_read2st64_b32 v[248:249], v4 offset0:2 offset1:3
	v_mov_b32_e32 v16, v7
	v_mov_b32_e32 v17, v7
	v_mov_b32_e32 v8, v7
	v_mov_b32_e32 v9, v7
	s_waitcnt lgkmcnt(2)
	v_add_f32_e32 v2, v2, v3
	v_fmamk_f32 v2, v2, 0x3c800000, v232
	v_rsq_f32_e32 v6, v2
	v_mov_b32_e32 v10, v7
	v_mov_b32_e32 v11, v7
	v_mov_b32_e32 v12, v7
	s_waitcnt lgkmcnt(1)
	v_pk_add_f32 v[2:3], v[114:115], v[246:247]
	s_waitcnt lgkmcnt(0)
	v_pk_add_f32 v[4:5], v[116:117], v[248:249]
	v_pk_mul_f32 v[2:3], v[2:3], v[6:7] op_sel_hi:[1,0]
	v_pk_mul_f32 v[4:5], v[6:7], v[4:5] op_sel_hi:[0,1]
	v_mov_b32_e32 v6, v7
	v_mov_b32_e32 v13, v7
	v_mov_b32_e32 v14, v7
	v_mov_b32_e32 v15, v7
	v_mov_b64_e32 v[112:113], v[16:17]
	v_mov_b64_e32 v[110:111], v[14:15]
	v_mov_b64_e32 v[108:109], v[12:13]
	v_mov_b64_e32 v[106:107], v[10:11]
	v_mov_b64_e32 v[104:105], v[8:9]
	v_mov_b64_e32 v[102:103], v[6:7]
	v_mov_b64_e32 v[100:101], v[4:5]
	v_mov_b64_e32 v[98:99], v[2:3]
	v_mul_lo_u32 v2, v244, s81
	v_lshl_or_b32 v2, v243, 1, v2
	v_mfma_f32_32x32x16_bf16 v[98:113], v[222:225], v[130:133], v[98:113]
	s_add_i32 s0, s13, s93
	v_add_u32_e32 v2, s0, v2
	v_add_u32_e32 v3, 0x27800, v2
	v_mfma_f32_32x32x16_bf16 v[98:113], v[218:221], v[134:137], v[98:113]
	s_nop 11
	v_sub_f32_e32 v4, v98, v230
	v_cmp_gt_f32_e32 vcc, s31, v4
	s_nop 1
	v_cndmask_b32_e32 v5, 0, v233, vcc
	v_add_f32_e32 v4, v4, v5
	v_exp_f32_e32 v4, v4
	v_cndmask_b32_e32 v5, 0, v241, vcc
	v_ldexp_f32 v4, v4, v5
	v_cvt_pk_bf16_f32 v4, v4, v7
	ds_write_b16 v3, v4
	v_sub_f32_e32 v3, v99, v230
	v_cmp_gt_f32_e32 vcc, s31, v3
	s_nop 1
	v_cndmask_b32_e32 v4, 0, v233, vcc
	v_add_f32_e32 v3, v3, v4
	v_exp_f32_e32 v3, v3
	v_cndmask_b32_e32 v4, 0, v241, vcc
	v_ldexp_f32 v3, v3, v4
	v_cvt_pk_bf16_f32 v3, v3, v7
	v_add_u32_e32 v4, 0x27910, v2
	ds_write_b16 v4, v3
	v_sub_f32_e32 v3, v100, v230
	v_cmp_gt_f32_e32 vcc, s31, v3
	s_nop 1
	v_cndmask_b32_e32 v4, 0, v233, vcc
	v_add_f32_e32 v3, v3, v4
	v_exp_f32_e32 v3, v3
	v_cndmask_b32_e32 v4, 0, v241, vcc
	v_ldexp_f32 v3, v3, v4
	v_cvt_pk_bf16_f32 v3, v3, v7
	v_add_u32_e32 v4, 0x27a20, v2
	ds_write_b16 v4, v3
	v_sub_f32_e32 v3, v101, v230
	v_cmp_gt_f32_e32 vcc, s31, v3
	v_add_u32_e32 v2, 0x27b30, v2
	s_nop 0
	v_cndmask_b32_e32 v4, 0, v233, vcc
	v_add_f32_e32 v3, v3, v4
	v_exp_f32_e32 v3, v3
	v_cndmask_b32_e32 v4, 0, v241, vcc
	v_ldexp_f32 v3, v3, v4
	v_cvt_pk_bf16_f32 v3, v3, v7
	ds_write_b16 v2, v3
	s_branch .LBB0_1557

.LBB0_1596:
	s_or_b64 exec, exec, s[0:1]
	s_and_b32 s0, s82, 0x3c000
	s_lshl_b32 s0, s0, 1
	s_add_u32 s0, s64, s0
	s_addc_u32 s1, s65, 0
	v_lshl_add_u32 v6, v12, 4, s76
	v_lshl_add_u64 v[14:15], s[0:1], 0, v[6:7]
	v_add_co_u32_e32 v16, vcc, s87, v14
	global_load_dwordx4 v[138:141], v6, s[0:1]
	s_nop 0
	v_addc_co_u32_e32 v17, vcc, 0, v15, vcc
	global_load_dwordx4 v[142:145], v[16:17], off
	v_add_co_u32_e32 v16, vcc, s4, v14
	v_lshlrev_b32_e32 v13, 4, v244
	s_nop 0
	v_addc_co_u32_e32 v17, vcc, 0, v15, vcc
	v_add_co_u32_e32 v14, vcc, s5, v14
	global_load_dwordx4 v[146:149], v[16:17], off
	s_nop 0
	v_addc_co_u32_e32 v15, vcc, 0, v15, vcc
	global_load_dwordx4 v[150:153], v[14:15], off
	s_mul_i32 s0, s95, 0x8200
	s_add_i32 s0, s0, 0
	s_add_i32 s0, s0, s54
	v_mul_u32_u24_e32 v6, 0x410, v243
	s_add_i32 s0, s0, 0x10800
	v_add3_u32 v6, s0, v6, v13
	ds_read_b128 v[114:117], v6
	ds_read_b128 v[118:121], v6 offset:32
	ds_read_b128 v[122:125], v6 offset:64
	ds_read_b128 v[126:129], v6 offset:96
	ds_read_b128 v[14:17], v6 offset:128
	s_waitcnt lgkmcnt(4)
	v_mfma_f32_32x32x16_bf16 v[98:113], v[114:117], v[154:157], 0
	ds_read_b128 v[114:117], v6 offset:160
	s_waitcnt lgkmcnt(4)
	v_mfma_f32_32x32x16_bf16 v[98:113], v[118:121], v[158:161], v[98:113]
	ds_read_b128 v[118:121], v6 offset:192
	s_waitcnt lgkmcnt(4)
	v_mfma_f32_32x32x16_bf16 v[98:113], v[122:125], v[162:165], v[98:113]
	ds_read_b128 v[122:125], v6 offset:224
	s_waitcnt lgkmcnt(4)
	v_mfma_f32_32x32x16_bf16 v[98:113], v[126:129], v[166:169], v[98:113]
	ds_read_b128 v[126:129], v6 offset:256
	s_waitcnt lgkmcnt(4)
	v_mfma_f32_32x32x16_bf16 v[98:113], v[14:17], v[170:173], v[98:113]
	ds_read_b128 v[14:17], v6 offset:288
	s_waitcnt lgkmcnt(4)
	v_mfma_f32_32x32x16_bf16 v[98:113], v[114:117], v[174:177], v[98:113]
	ds_read_b128 v[114:117], v6 offset:320
	s_waitcnt lgkmcnt(4)
	v_mfma_f32_32x32x16_bf16 v[98:113], v[118:121], v[178:181], v[98:113]
	ds_read_b128 v[118:121], v6 offset:352
	s_waitcnt lgkmcnt(4)
	v_mfma_f32_32x32x16_bf16 v[98:113], v[122:125], v[182:185], v[98:113]
	ds_read_b128 v[122:125], v6 offset:384
	s_waitcnt lgkmcnt(4)
	v_mfma_f32_32x32x16_bf16 v[98:113], v[126:129], v[186:189], v[98:113]
	ds_read_b128 v[126:129], v6 offset:416
	s_waitcnt lgkmcnt(4)
	v_mfma_f32_32x32x16_bf16 v[98:113], v[14:17], v[190:193], v[98:113]
	ds_read_b128 v[14:17], v6 offset:448
	s_waitcnt lgkmcnt(4)
	v_mfma_f32_32x32x16_bf16 v[98:113], v[114:117], v[194:197], v[98:113]
	ds_read_b128 v[114:117], v6 offset:480
	s_waitcnt lgkmcnt(4)
	v_mfma_f32_32x32x16_bf16 v[98:113], v[118:121], v[198:201], v[98:113]
	s_waitcnt lgkmcnt(3)
	v_mfma_f32_32x32x16_bf16 v[98:113], v[122:125], v[202:205], v[98:113]
	s_waitcnt lgkmcnt(2)
	v_mfma_f32_32x32x16_bf16 v[98:113], v[126:129], v[206:209], v[98:113]
	s_waitcnt lgkmcnt(1)
	v_mfma_f32_32x32x16_bf16 v[98:113], v[14:17], v[210:213], v[98:113]
	s_waitcnt lgkmcnt(0)
	v_mfma_f32_32x32x16_bf16 v[98:113], v[114:117], v[214:217], v[98:113]
	s_nop 11
	v_mul_f32_e32 v6, v99, v99
	v_fmac_f32_e32 v6, v98, v98
	v_fmac_f32_e32 v6, v100, v100
	v_fmac_f32_e32 v6, v101, v101
	v_fmac_f32_e32 v6, v102, v102
	v_fmac_f32_e32 v6, v103, v103
	v_fmac_f32_e32 v6, v104, v104
	v_cvt_pk_bf16_f32 v14, v98, v99
	v_cvt_pk_bf16_f32 v15, v100, v101
	v_cvt_pk_bf16_f32 v16, v102, v103
	v_cvt_pk_bf16_f32 v17, v104, v105
	v_fmac_f32_e32 v6, v105, v105
	s_waitcnt vmcnt(5)
	v_mfma_f32_32x32x16_bf16 v[114:129], v[8:11], v[14:17], 0
	v_fmac_f32_e32 v6, v106, v106
	v_fmac_f32_e32 v6, v107, v107
	v_fmac_f32_e32 v6, v108, v108
	v_fmac_f32_e32 v6, v109, v109
	v_fmac_f32_e32 v6, v110, v110
	v_fmac_f32_e32 v6, v111, v111
	v_fmac_f32_e32 v6, v112, v112
	v_cvt_pk_bf16_f32 v8, v106, v107
	v_cvt_pk_bf16_f32 v9, v108, v109
	v_cvt_pk_bf16_f32 v10, v110, v111
	v_cvt_pk_bf16_f32 v11, v112, v113
	v_fmac_f32_e32 v6, v113, v113
	s_waitcnt vmcnt(4)
	v_mfma_f32_32x32x16_bf16 v[114:129], v[2:5], v[8:11], v[114:129]
	v_mov_b32_e32 v245, v6
	s_mulk_i32 s95, 0x1400
	s_add_i32 s0, s77, s95
	s_and_b64 vcc, exec, s[8:9]
	v_lshl_add_u32 v4, v12, 2, s0
	v_permlane32_swap_b32_e32 v245, v6
	v_add_f32_e32 v2, v245, v6
	s_cbranch_vccnz .LBB0_1598
	s_nop 3
	ds_write2st64_b32 v4, v114, v115 offset1:1
	ds_write2st64_b32 v4, v116, v117 offset0:2 offset1:3
	ds_write_b32 v4, v2 offset:1024
.LBB0_1598:
	s_waitcnt lgkmcnt(0)
	s_barrier
	s_and_b64 vcc, exec, s[6:7]
	s_cbranch_vccnz .LBB0_1587
	ds_read_b32 v3, v4 offset:1024
	ds_read2st64_b32 v[246:247], v4 offset1:1
	ds_read2st64_b32 v[248:249], v4 offset0:2 offset1:3
	v_mov_b32_e32 v16, v7
	v_mov_b32_e32 v17, v7
	v_mov_b32_e32 v8, v7
	v_mov_b32_e32 v9, v7
	s_waitcnt lgkmcnt(2)
	v_add_f32_e32 v2, v2, v3
	v_fmamk_f32 v2, v2, 0x3c800000, v232
	v_rsq_f32_e32 v6, v2
	v_mov_b32_e32 v10, v7
	v_mov_b32_e32 v11, v7
	v_mov_b32_e32 v12, v7
	s_waitcnt lgkmcnt(1)
	v_pk_add_f32 v[2:3], v[114:115], v[246:247]
	s_waitcnt lgkmcnt(0)
	v_pk_add_f32 v[4:5], v[116:117], v[248:249]
	v_pk_mul_f32 v[2:3], v[2:3], v[6:7] op_sel_hi:[1,0]
	v_pk_mul_f32 v[4:5], v[6:7], v[4:5] op_sel_hi:[0,1]
	v_mov_b32_e32 v6, v7
	v_mov_b32_e32 v13, v7
	v_mov_b32_e32 v14, v7
	v_mov_b32_e32 v15, v7
	v_mov_b64_e32 v[112:113], v[16:17]
	v_mov_b64_e32 v[110:111], v[14:15]
	v_mov_b64_e32 v[108:109], v[12:13]
	v_mov_b64_e32 v[106:107], v[10:11]
	v_mov_b64_e32 v[104:105], v[8:9]
	v_mov_b64_e32 v[102:103], v[6:7]
	v_mov_b64_e32 v[100:101], v[4:5]
	v_mov_b64_e32 v[98:99], v[2:3]
	v_mul_lo_u32 v2, v244, s81
	v_lshl_or_b32 v2, v243, 1, v2
	v_mfma_f32_32x32x16_bf16 v[98:113], v[222:225], v[130:133], v[98:113]
	s_add_i32 s0, s92, s93
	v_add_u32_e32 v2, s0, v2
	v_add_u32_e32 v3, 0x25600, v2
	v_mfma_f32_32x32x16_bf16 v[98:113], v[218:221], v[134:137], v[98:113]
	s_nop 11
	v_sub_f32_e32 v4, v98, v230
	v_cmp_gt_f32_e32 vcc, s31, v4
	s_nop 1
	v_cndmask_b32_e32 v5, 0, v233, vcc
	v_add_f32_e32 v4, v4, v5
	v_exp_f32_e32 v4, v4
	v_cndmask_b32_e32 v5, 0, v241, vcc
	v_ldexp_f32 v4, v4, v5
	v_cvt_pk_bf16_f32 v4, v4, v7
	ds_write_b16 v3, v4
	v_sub_f32_e32 v3, v99, v230
	v_cmp_gt_f32_e32 vcc, s31, v3
	s_nop 1
	v_cndmask_b32_e32 v4, 0, v233, vcc
	v_add_f32_e32 v3, v3, v4
	v_exp_f32_e32 v3, v3
	v_cndmask_b32_e32 v4, 0, v241, vcc
	v_ldexp_f32 v3, v3, v4
	v_cvt_pk_bf16_f32 v3, v3, v7
	v_add_u32_e32 v4, 0x25710, v2
	ds_write_b16 v4, v3
	v_sub_f32_e32 v3, v100, v230
	v_cmp_gt_f32_e32 vcc, s31, v3
	s_nop 1
	v_cndmask_b32_e32 v4, 0, v233, vcc
	v_add_f32_e32 v3, v3, v4
	v_exp_f32_e32 v3, v3
	v_cndmask_b32_e32 v4, 0, v241, vcc
	v_ldexp_f32 v3, v3, v4
	v_cvt_pk_bf16_f32 v3, v3, v7
	v_add_u32_e32 v4, 0x25820, v2
	ds_write_b16 v4, v3
	v_sub_f32_e32 v3, v101, v230
	v_cmp_gt_f32_e32 vcc, s31, v3
	v_add_u32_e32 v2, 0x25930, v2
	s_nop 0
	v_cndmask_b32_e32 v4, 0, v233, vcc
	v_add_f32_e32 v3, v3, v4
	v_exp_f32_e32 v3, v3
	v_cndmask_b32_e32 v4, 0, v241, vcc
	v_ldexp_f32 v3, v3, v4
	v_cvt_pk_bf16_f32 v3, v3, v7
	ds_write_b16 v2, v3
	s_branch .LBB0_1587

.LBB0_1626:
	s_or_b64 exec, exec, s[0:1]
	s_and_b32 s0, s95, 0x3c000
	s_lshl_b32 s0, s0, 1
	s_add_u32 s0, s64, s0
	s_addc_u32 s1, s65, 0
	v_lshl_add_u32 v6, v12, 4, s76
	v_lshl_add_u64 v[14:15], s[0:1], 0, v[6:7]
	v_add_co_u32_e32 v16, vcc, s87, v14
	global_load_dwordx4 v[138:141], v6, s[0:1]
	s_nop 0
	v_addc_co_u32_e32 v17, vcc, 0, v15, vcc
	global_load_dwordx4 v[142:145], v[16:17], off
	v_add_co_u32_e32 v16, vcc, s4, v14
	v_lshlrev_b32_e32 v13, 4, v244
	s_nop 0
	v_addc_co_u32_e32 v17, vcc, 0, v15, vcc
	v_add_co_u32_e32 v14, vcc, s5, v14
	global_load_dwordx4 v[146:149], v[16:17], off
	s_nop 0
	v_addc_co_u32_e32 v15, vcc, 0, v15, vcc
	global_load_dwordx4 v[150:153], v[14:15], off
	s_mul_i32 s0, s78, 0x8200
	s_add_i32 s0, s0, 0
	s_add_i32 s0, s0, s54
	v_mul_u32_u24_e32 v6, 0x410, v243
	s_add_i32 s0, s0, 0x10800
	v_add3_u32 v6, s0, v6, v13
	ds_read_b128 v[114:117], v6
	ds_read_b128 v[118:121], v6 offset:32
	ds_read_b128 v[122:125], v6 offset:64
	ds_read_b128 v[126:129], v6 offset:96
	ds_read_b128 v[14:17], v6 offset:128
	s_waitcnt lgkmcnt(4)
	v_mfma_f32_32x32x16_bf16 v[98:113], v[114:117], v[154:157], 0
	ds_read_b128 v[114:117], v6 offset:160
	s_waitcnt lgkmcnt(4)
	v_mfma_f32_32x32x16_bf16 v[98:113], v[118:121], v[158:161], v[98:113]
	ds_read_b128 v[118:121], v6 offset:192
	s_waitcnt lgkmcnt(4)
	v_mfma_f32_32x32x16_bf16 v[98:113], v[122:125], v[162:165], v[98:113]
	ds_read_b128 v[122:125], v6 offset:224
	s_waitcnt lgkmcnt(4)
	v_mfma_f32_32x32x16_bf16 v[98:113], v[126:129], v[166:169], v[98:113]
	ds_read_b128 v[126:129], v6 offset:256
	s_waitcnt lgkmcnt(4)
	v_mfma_f32_32x32x16_bf16 v[98:113], v[14:17], v[170:173], v[98:113]
	ds_read_b128 v[14:17], v6 offset:288
	s_waitcnt lgkmcnt(4)
	v_mfma_f32_32x32x16_bf16 v[98:113], v[114:117], v[174:177], v[98:113]
	ds_read_b128 v[114:117], v6 offset:320
	s_waitcnt lgkmcnt(4)
	v_mfma_f32_32x32x16_bf16 v[98:113], v[118:121], v[178:181], v[98:113]
	ds_read_b128 v[118:121], v6 offset:352
	s_waitcnt lgkmcnt(4)
	v_mfma_f32_32x32x16_bf16 v[98:113], v[122:125], v[182:185], v[98:113]
	ds_read_b128 v[122:125], v6 offset:384
	s_waitcnt lgkmcnt(4)
	v_mfma_f32_32x32x16_bf16 v[98:113], v[126:129], v[186:189], v[98:113]
	ds_read_b128 v[126:129], v6 offset:416
	s_waitcnt lgkmcnt(4)
	v_mfma_f32_32x32x16_bf16 v[98:113], v[14:17], v[190:193], v[98:113]
	ds_read_b128 v[14:17], v6 offset:448
	s_waitcnt lgkmcnt(4)
	v_mfma_f32_32x32x16_bf16 v[98:113], v[114:117], v[194:197], v[98:113]
	ds_read_b128 v[114:117], v6 offset:480
	s_waitcnt lgkmcnt(4)
	v_mfma_f32_32x32x16_bf16 v[98:113], v[118:121], v[198:201], v[98:113]
	s_waitcnt lgkmcnt(3)
	v_mfma_f32_32x32x16_bf16 v[98:113], v[122:125], v[202:205], v[98:113]
	s_waitcnt lgkmcnt(2)
	v_mfma_f32_32x32x16_bf16 v[98:113], v[126:129], v[206:209], v[98:113]
	s_waitcnt lgkmcnt(1)
	v_mfma_f32_32x32x16_bf16 v[98:113], v[14:17], v[210:213], v[98:113]
	s_waitcnt lgkmcnt(0)
	v_mfma_f32_32x32x16_bf16 v[98:113], v[114:117], v[214:217], v[98:113]
	s_nop 11
	v_mul_f32_e32 v6, v99, v99
	v_fmac_f32_e32 v6, v98, v98
	v_fmac_f32_e32 v6, v100, v100
	v_fmac_f32_e32 v6, v101, v101
	v_fmac_f32_e32 v6, v102, v102
	v_fmac_f32_e32 v6, v103, v103
	v_fmac_f32_e32 v6, v104, v104
	v_cvt_pk_bf16_f32 v14, v98, v99
	v_cvt_pk_bf16_f32 v15, v100, v101
	v_cvt_pk_bf16_f32 v16, v102, v103
	v_cvt_pk_bf16_f32 v17, v104, v105
	v_fmac_f32_e32 v6, v105, v105
	s_waitcnt vmcnt(5)
	v_mfma_f32_32x32x16_bf16 v[114:129], v[8:11], v[14:17], 0
	v_fmac_f32_e32 v6, v106, v106
	v_fmac_f32_e32 v6, v107, v107
	v_fmac_f32_e32 v6, v108, v108
	v_fmac_f32_e32 v6, v109, v109
	v_fmac_f32_e32 v6, v110, v110
	v_fmac_f32_e32 v6, v111, v111
	v_fmac_f32_e32 v6, v112, v112
	v_cvt_pk_bf16_f32 v8, v106, v107
	v_cvt_pk_bf16_f32 v9, v108, v109
	v_cvt_pk_bf16_f32 v10, v110, v111
	v_cvt_pk_bf16_f32 v11, v112, v113
	v_fmac_f32_e32 v6, v113, v113
	s_waitcnt vmcnt(4)
	v_mfma_f32_32x32x16_bf16 v[114:129], v[2:5], v[8:11], v[114:129]
	v_mov_b32_e32 v245, v6
	s_mulk_i32 s78, 0x1400
	s_add_i32 s0, s77, s78
	s_and_b64 vcc, exec, s[8:9]
	v_lshl_add_u32 v4, v12, 2, s0
	v_permlane32_swap_b32_e32 v245, v6
	v_add_f32_e32 v2, v245, v6
	s_cbranch_vccnz .LBB0_1628
	s_nop 3
	ds_write2st64_b32 v4, v114, v115 offset1:1
	ds_write2st64_b32 v4, v116, v117 offset0:2 offset1:3
	ds_write_b32 v4, v2 offset:1024
.LBB0_1628:
	s_waitcnt lgkmcnt(0)
	s_barrier
	s_and_b64 vcc, exec, s[6:7]
	s_cbranch_vccnz .LBB0_1617
	ds_read_b32 v3, v4 offset:1024
	ds_read2st64_b32 v[246:247], v4 offset1:1
	ds_read2st64_b32 v[248:249], v4 offset0:2 offset1:3
	v_mov_b32_e32 v16, v7
	v_mov_b32_e32 v17, v7
	v_mov_b32_e32 v8, v7
	v_mov_b32_e32 v9, v7
	s_waitcnt lgkmcnt(2)
	v_add_f32_e32 v2, v2, v3
	v_fmamk_f32 v2, v2, 0x3c800000, v232
	v_rsq_f32_e32 v6, v2
	v_mov_b32_e32 v10, v7
	v_mov_b32_e32 v11, v7
	v_mov_b32_e32 v12, v7
	s_waitcnt lgkmcnt(1)
	v_pk_add_f32 v[2:3], v[114:115], v[246:247]
	s_waitcnt lgkmcnt(0)
	v_pk_add_f32 v[4:5], v[116:117], v[248:249]
	v_pk_mul_f32 v[2:3], v[2:3], v[6:7] op_sel_hi:[1,0]
	v_pk_mul_f32 v[4:5], v[6:7], v[4:5] op_sel_hi:[0,1]
	v_mov_b32_e32 v6, v7
	v_mov_b32_e32 v13, v7
	v_mov_b32_e32 v14, v7
	v_mov_b32_e32 v15, v7
	v_mov_b64_e32 v[112:113], v[16:17]
	v_mov_b64_e32 v[110:111], v[14:15]
	v_mov_b64_e32 v[108:109], v[12:13]
	v_mov_b64_e32 v[106:107], v[10:11]
	v_mov_b64_e32 v[104:105], v[8:9]
	v_mov_b64_e32 v[102:103], v[6:7]
	v_mov_b64_e32 v[100:101], v[4:5]
	v_mov_b64_e32 v[98:99], v[2:3]
	v_mul_lo_u32 v2, v244, s81
	v_lshl_or_b32 v2, v243, 1, v2
	v_mfma_f32_32x32x16_bf16 v[98:113], v[222:225], v[130:133], v[98:113]
	s_add_i32 s0, s82, s93
	v_add_u32_e32 v2, s0, v2
	v_add_u32_e32 v3, 0x27800, v2
	v_mfma_f32_32x32x16_bf16 v[98:113], v[218:221], v[134:137], v[98:113]
	s_nop 11
	v_sub_f32_e32 v4, v98, v230
	v_cmp_gt_f32_e32 vcc, s31, v4
	s_nop 1
	v_cndmask_b32_e32 v5, 0, v233, vcc
	v_add_f32_e32 v4, v4, v5
	v_exp_f32_e32 v4, v4
	v_cndmask_b32_e32 v5, 0, v241, vcc
	v_ldexp_f32 v4, v4, v5
	v_cvt_pk_bf16_f32 v4, v4, v7
	ds_write_b16 v3, v4
	v_sub_f32_e32 v3, v99, v230
	v_cmp_gt_f32_e32 vcc, s31, v3
	s_nop 1
	v_cndmask_b32_e32 v4, 0, v233, vcc
	v_add_f32_e32 v3, v3, v4
	v_exp_f32_e32 v3, v3
	v_cndmask_b32_e32 v4, 0, v241, vcc
	v_ldexp_f32 v3, v3, v4
	v_cvt_pk_bf16_f32 v3, v3, v7
	v_add_u32_e32 v4, 0x27910, v2
	ds_write_b16 v4, v3
	v_sub_f32_e32 v3, v100, v230
	v_cmp_gt_f32_e32 vcc, s31, v3
	s_nop 1
	v_cndmask_b32_e32 v4, 0, v233, vcc
	v_add_f32_e32 v3, v3, v4
	v_exp_f32_e32 v3, v3
	v_cndmask_b32_e32 v4, 0, v241, vcc
	v_ldexp_f32 v3, v3, v4
	v_cvt_pk_bf16_f32 v3, v3, v7
	v_add_u32_e32 v4, 0x27a20, v2
	ds_write_b16 v4, v3
	v_sub_f32_e32 v3, v101, v230
	v_cmp_gt_f32_e32 vcc, s31, v3
	v_add_u32_e32 v2, 0x27b30, v2
	s_nop 0
	v_cndmask_b32_e32 v4, 0, v233, vcc
	v_add_f32_e32 v3, v3, v4
	v_exp_f32_e32 v3, v3
	v_cndmask_b32_e32 v4, 0, v241, vcc
	v_ldexp_f32 v3, v3, v4
	v_cvt_pk_bf16_f32 v3, v3, v7
	ds_write_b16 v2, v3
	s_branch .LBB0_1617
